# stick-breaking units: all 512 in one q-block-descending order, first ticket blockIdx, rest from the counter (long units first everywhere)
# baseline (speedup 1.0000x reference)
.LBB0_582:
	s_cmpk_gt_i32 s3, 0x1ff
	s_cbranch_scc1 .LBB0_601
	v_mbcnt_lo_u32_b32 v0, -1, 0
	s_movk_i32 s44, 0x3000
	s_waitcnt vmcnt(3)
	v_mov_b64_e32 v[146:147], s[12:13]
	s_mov_b32 s9, 0
	v_mov_b32_e32 v1, 0
	s_mov_b32 s45, 0xc000
	s_movk_i32 s46, 0x2000
	s_movk_i32 s47, 0x110
	s_movk_i32 s48, 0x90
	s_mov_b32 s49, 0x43180000
	s_movk_i32 s50, 0x1000
	s_mov_b32 s51, 0xd000
	s_mov_b32 s52, 0x19000
	s_mov_b32 s53, 0x25000
	s_mov_b32 s54, 0x31000
	s_mov_b32 s55, 0x3d000
	s_mov_b32 s56, 0x49000
	s_mov_b32 s57, 0x55000
	s_movk_i32 s58, 0x4000
	s_mov_b32 s59, 0x8000
	s_mov_b32 s60, 0x10000
	s_mov_b32 s61, 0x14000
	s_mov_b32 s62, 0x18000
	v_mov_b32_e32 v194, 0xf149f2ca
	v_mbcnt_hi_u32_b32 v195, -1, v0
	s_cmpk_lg_u32 s24, 0x100
	s_cbranch_scc1 .Lsq_nomap
	s_and_b32 s96, s3, 63
	s_lshl_b32 s96, s96, 3
	s_lshr_b32 s97, s3, 6
	s_sub_i32 s97, 7, s97
	s_or_b32 s3, s96, s97
.Lsq_nomap:
	v_mov_b32_e32 v196, 0x3000
	s_mov_b32 s63, s3
	s_branch .LBB0_585

.Lsq_nw:
	s_barrier
	ds_read_b32 v237, v236
	s_waitcnt lgkmcnt(0)
	v_readfirstlane_b32 s97, v237
	s_nop 3
	s_cmpk_gt_u32 s97, 0xff
	s_cbranch_scc1 .LBB0_601
	s_addk_i32 s97, 0x100
	s_and_b32 s96, s97, 63
	s_lshl_b32 s96, s96, 3
	s_lshr_b32 s3, s97, 6
	s_sub_i32 s3, 7, s3
	s_or_b32 s3, s3, s96
	s_mov_b32 s63, s3
	s_branch .LBB0_585

.Lsq_noat:
	s_lshl_b32 s65, s4, 8
	s_ashr_i32 s4, s3, 6
	s_lshl_b32 s5, s42, 8
	s_lshl_b32 s66, s64, 5
	s_add_i32 s66, s66, s5
	s_ashr_i32 s5, s4, 31
	s_bfe_u32 s8, s3, 0x30003
	v_and_b32_e32 v7, 31, v6
	s_lshl_b64 s[38:39], s[4:5], 11
	s_lshl_b32 s4, s4, 3
	s_waitcnt vmcnt(2)
	v_or_b32_e32 v150, s66, v7
	s_or_b32 s4, s4, s8
	s_ashr_i32 s5, s4, 31
	v_ashrrev_i32_e32 v151, 31, v150
	s_lshl_b64 s[4:5], s[4:5], 19
	v_lshl_add_u64 v[2:3], s[38:39], 0, v[150:151]
	s_add_u32 s6, s14, s4
	v_mad_u64_u32 v[4:5], s[40:41], v2, s44, v[146:147]
	v_bfe_u32 v8, v6, 5, 1
	s_addc_u32 s7, s15, s5
	v_mad_i32_i24 v5, v3, s44, v5
	s_lshl_b32 s67, s8, 7
	s_lshl_b32 s8, s8, 8
	v_lshl_add_u64 v[2:3], v[4:5], 0, s[8:9]
	v_lshlrev_b32_e32 v0, 4, v8
	v_lshl_add_u64 v[2:3], v[2:3], 0, v[0:1]
	global_load_dwordx4 v[98:101], v[2:3], off
	global_load_dwordx4 v[102:105], v[2:3], off offset:32
	global_load_dwordx4 v[106:109], v[2:3], off offset:64
	global_load_dwordx4 v[110:113], v[2:3], off offset:96
	global_load_dwordx4 v[114:117], v[2:3], off offset:128
	global_load_dwordx4 v[118:121], v[2:3], off offset:160
	global_load_dwordx4 v[122:125], v[2:3], off offset:192
	global_load_dwordx4 v[126:129], v[2:3], off offset:224
	v_lshlrev_b32_e32 v2, 3, v6
	s_add_u32 s4, s81, s4
	v_ashrrev_i32_e32 v3, 31, v2
	s_addc_u32 s5, s82, s5
	v_lshlrev_b64 v[2:3], 1, v[2:3]
	v_mov_b32_e32 v228, v2
	v_add_u32_e32 v229, 0x2000, v2
	s_waitcnt vmcnt(9)
	s_mov_b64 s[90:91], s[4:5]
	v_lshl_add_u64 v[154:155], s[4:5], 0, v[2:3]
	s_lshl_b32 s4, s42, 16
	s_mov_b64 s[88:89], s[6:7]
	v_lshl_add_u64 v[152:153], s[6:7], 0, v[2:3]
	s_or_b32 s8, s4, 0xc000
	v_lshl_add_u64 v[2:3], v[152:153], 0, s[8:9]
	s_barrier
	v_lshl_add_u64 v[4:5], v[154:155], 0, s[8:9]
	global_load_dwordx4 v[130:133], v[2:3], off
	global_load_dwordx4 v[134:137], v[4:5], off
	v_add_co_u32_e32 v2, vcc, s46, v2
	v_and_b32_e32 v149, 63, v6
	s_nop 0
	v_addc_co_u32_e32 v3, vcc, 0, v3, vcc
	v_add_co_u32_e32 v4, vcc, s46, v4
	v_mul_u32_u24_e32 v197, 0x110, v7
	s_nop 0
	v_addc_co_u32_e32 v5, vcc, 0, v5, vcc
	global_load_dwordx4 v[138:141], v[2:3], off
	global_load_dwordx4 v[142:145], v[4:5], off
	v_lshlrev_b32_e32 v2, 4, v6
	v_lshrrev_b32_e32 v3, 3, v6
	v_lshrrev_b32_e32 v4, 4, v6
	v_and_b32_e32 v148, 0xf0, v2
	v_and_b32_e32 v2, 0x70, v2
	s_waitcnt vmcnt(12)
	v_mad_u64_u32 v[156:157], s[4:5], v4, s47, v[148:149]
	v_mad_u64_u32 v[158:159], s[4:5], v3, s48, v[2:3]
	v_lshlrev_b32_e32 v5, 7, v7
	v_add3_u32 v157, 0, v197, v0
	v_add_u32_e32 v0, 0, v156
	v_add_u32_e32 v2, 0, v158
	v_mov_b32_e32 v14, v1
	v_mov_b32_e32 v15, v1
	v_lshlrev_b32_e32 v151, 3, v8
	s_lshl_b32 s4, s64, 2
	v_lshlrev_b32_e32 v159, 2, v8
	v_sub_u32_e32 v198, v157, v5
	v_mov_b32_e32 v3, v1
	v_mov_b32_e32 v4, v1
	v_mov_b32_e32 v5, v1
	v_mov_b32_e32 v6, v1
	v_mov_b32_e32 v7, v1
	v_mov_b32_e32 v8, v1
	v_mov_b32_e32 v9, v1
	v_mov_b32_e32 v10, v1
	v_mov_b32_e32 v11, v1
	v_mov_b32_e32 v12, v1
	v_mov_b32_e32 v13, v1
	s_add_i32 s69, s4, 0
	v_cmp_eq_u32_e64 s[6:7], 0, v149
	s_or_b32 s68, s66, 30
	s_add_i32 s69, s69, 0x11800
	v_cmp_gt_u32_e64 s[4:5], 32, v149
	s_mov_b64 s[42:43], 0
	s_mov_b32 s70, s9
	s_mov_b32 s8, s71
	s_mov_b32 s71, s9
	s_waitcnt vmcnt(3)
	ds_write_b128 v0, v[130:133]
	s_waitcnt vmcnt(2)
	ds_write_b128 v2, v[134:137] offset:17408
	s_waitcnt vmcnt(1)
	ds_write_b128 v0, v[138:141] offset:8704
	s_waitcnt vmcnt(0)
	ds_write_b128 v2, v[142:145] offset:26624
	v_mov_b32_e32 v0, v1
	v_mov_b32_e32 v2, v1
	v_mov_b64_e32 v[64:65], v[14:15]
	v_mov_b64_e32 v[48:49], v[14:15]
	v_mov_b64_e32 v[32:33], v[14:15]
	v_mov_b64_e32 v[62:63], v[12:13]
	v_mov_b64_e32 v[60:61], v[10:11]
	v_mov_b64_e32 v[58:59], v[8:9]
	v_mov_b64_e32 v[56:57], v[6:7]
	v_mov_b64_e32 v[54:55], v[4:5]
	v_mov_b64_e32 v[52:53], v[2:3]
	v_mov_b64_e32 v[50:51], v[0:1]
	v_mov_b64_e32 v[46:47], v[12:13]
	v_mov_b64_e32 v[44:45], v[10:11]
	v_mov_b64_e32 v[42:43], v[8:9]
	v_mov_b64_e32 v[40:41], v[6:7]
	v_mov_b64_e32 v[38:39], v[4:5]
	v_mov_b64_e32 v[36:37], v[2:3]
	v_mov_b64_e32 v[34:35], v[0:1]
	v_mov_b64_e32 v[30:31], v[12:13]
	v_mov_b64_e32 v[28:29], v[10:11]
	v_mov_b64_e32 v[26:27], v[8:9]
	v_mov_b64_e32 v[24:25], v[6:7]
	v_mov_b64_e32 v[22:23], v[4:5]
	v_mov_b64_e32 v[20:21], v[2:3]
	v_mov_b64_e32 v[18:19], v[0:1]
	v_mov_b64_e32 v[16:17], v[14:15]
	v_mov_b64_e32 v[14:15], v[12:13]
	v_mov_b64_e32 v[12:13], v[10:11]
	v_mov_b64_e32 v[10:11], v[8:9]
	v_mov_b64_e32 v[8:9], v[6:7]
	v_mov_b64_e32 v[6:7], v[4:5]
	v_mov_b64_e32 v[4:5], v[2:3]
	v_mov_b64_e32 v[2:3], v[0:1]
	v_mov_b32_e32 v0, 0
	s_waitcnt lgkmcnt(0)
	s_barrier
	s_branch .LBB0_587
	s_nop 0
	s_nop 0
	s_nop 0
	s_nop 0
	s_nop 0
	s_nop 0
	s_nop 0
	s_nop 0
	s_nop 0
	s_nop 0
	s_nop 0
	s_nop 0
	s_nop 0
	s_nop 0
	s_nop 0
	s_nop 0
	s_nop 0
	s_nop 0
	s_nop 0
	s_nop 0
	s_nop 0
	s_nop 0
	s_nop 0
	s_nop 0
	s_nop 0
	s_nop 0
	s_nop 0
	s_nop 0
	s_nop 0
	s_nop 0
	s_nop 0
	s_nop 0
	s_nop 0
	s_nop 0
	s_nop 0
	s_nop 0
	s_nop 0
.LBB0_586:
	s_and_b64 vcc, exec, s[40:41]
	s_cbranch_vccnz .LBB0_584
